# final epilogue: four partial sums loaded together (was three dependent round trips); rest as previous (fillrs, c8dist, pollinv, carry, sc1)
# baseline (speedup 1.0000x reference)
;     __device__ __forceinline__ void fused(AccT& acc, const Unit& u, int wr, int wc, int fr, int fq, PG8_LAS unsigned char* lds, int wid, int lane) const {
;     ...
;         asm volatile("s_waitcnt vmcnt(0) lgkmcnt(0)" ::: "memory"); __builtin_amdgcn_s_barrier(); asm volatile("" ::: "memory");
;         if (tid < 256) { const float* sl = ssp + (size_t)(u.pm * BM + tid) * 4; float s = 0.f;
; #pragma unroll
;             for (int t = 0; t < 4; ++t) s += __hip_atomic_load(sl + t, __ATOMIC_RELAXED, __HIP_MEMORY_SCOPE_AGENT);
;             RS[tid] = rsqrtf(s * (1.0f / DM) + RMS_EPS); }
.LBB0_607:
	s_waitcnt vmcnt(0) lgkmcnt(0)
	s_barrier
	s_lshl_b32 s5, s66, 8
	s_and_saveexec_b64 s[10:11], s[42:43]
	s_cbranch_execz .LBB0_609
	s_waitcnt lgkmcnt(0)
	v_add_u32_e32 v130, s5, v128
	v_readlane_b32 s8, v250, 30
	v_ashrrev_i32_e32 v131, 31, v130
	v_readlane_b32 s9, v250, 31
	v_lshl_add_u32 v128, v128, 2, 0
	s_nop 0
	v_lshl_add_u64 v[130:131], v[130:131], 4, s[8:9]
	global_load_dword v129, v[130:131], off sc1
	global_load_dword v132, v[130:131], off offset:4 sc1
	global_load_dword v133, v[130:131], off offset:8 sc1
	global_load_dword v134, v[130:131], off offset:12 sc1
	s_waitcnt vmcnt(0)
	v_add_f32_e32 v129, 0, v129
	v_add_f32_e32 v129, v129, v132
	v_add_f32_e32 v129, v129, v133
	v_add_f32_e32 v129, v129, v134
	v_fmamk_f32 v129, v129, 0x3a800000, v166
	v_cmp_gt_f32_e32 vcc, s40, v129
	v_mul_f32_e32 v130, 0x4b800000, v129
	s_nop 0
	v_cndmask_b32_e32 v129, v129, v130, vcc
	v_rsq_f32_e32 v129, v129
	s_nop 0
	v_mul_f32_e32 v130, 0x45800000, v129
	v_cndmask_b32_e32 v129, v129, v130, vcc
	ds_write_b32 v128, v129 offset:4096
